# attention loops software-pipelined: S0/S1 score blocks in v216-231/v232-247, S1-init under QK0 MFMAs, exp(S0) under QK1 MFMAs, next tile S0-init under last 8 PV MFMAs, s_nop 11 removed (bit-identical
# speedup vs baseline: 1.0134x; 1.0134x over previous
.LBB0_222:
	s_movk_i32 s6, 0x400
	s_waitcnt lgkmcnt(0)
	v_cmp_gt_i32_e32 vcc, s6, v2
	s_mov_b64 s[8:9], -1
	s_barrier
	s_and_saveexec_b64 s[96:97], vcc
	s_cbranch_execz .LBB0_215
	v_ashrrev_i32_e32 v3, 7, v2
	v_sub_u32_e32 v3, 8, v3
	v_cvt_f32_u32_e32 v3, v3
	s_mov_b32 s6, 0x42fc0000
	v_lshlrev_b32_e32 v4, 7, v2
	v_bfe_u32 v123, v2, 5, 2
	v_cmp_lt_f32_e32 vcc, s6, v3
	v_and_b32_e32 v126, 0xf80, v4
	v_or_b32_e32 v66, v126, v194
	v_cndmask_b32_e32 v5, 0, v206, vcc
	v_sub_f32_e32 v3, v5, v3
	v_exp_f32_e32 v3, v3
	v_lshlrev_b32_e32 v124, 12, v123
	v_or_b32_e32 v153, v66, v124
	v_cndmask_b32_e32 v4, 0, v207, vcc
	v_lshlrev_b32_e32 v132, 11, v153
	v_and_b32_e32 v2, 0xffffff80, v2
	v_ldexp_f32 v6, v3, v4
	v_lshl_add_u64 v[4:5], s[70:71], 0, v[132:133]
	v_sub_u32_e32 v158, 0x380, v2
	v_mov_b32_e32 v159, v133
	v_lshl_add_u64 v[2:3], v[158:159], 1, v[4:5]
	v_mov_b32_e32 v141, v133
	v_lshl_add_u64 v[2:3], v[2:3], 0, v[140:141]
	v_mov_b32_e32 v157, v133
	v_lshl_add_u64 v[2:3], v[2:3], 0, v[156:157]
	global_load_dwordx4 v[82:85], v[2:3], off
	global_load_dwordx4 v[86:89], v[2:3], off offset:32
	global_load_dwordx4 v[90:93], v[2:3], off offset:64
	global_load_dwordx4 v[94:97], v[2:3], off offset:96
	v_mul_f32_e32 v2, 0xbfb8aa3b, v6
	s_mov_b32 s6, 0xbfb8aa3b
	v_fma_f32 v3, v6, s6, -v2
	v_rndne_f32_e32 v4, v2
	v_fmac_f32_e32 v3, 0xb2a5705f, v6
	v_sub_f32_e32 v2, v2, v4
	v_add_f32_e32 v2, v2, v3
	v_exp_f32_e32 v2, v2
	v_cvt_i32_f32_e32 v3, v4
	s_mov_b32 s6, 0x42ce8ed0
	v_cmp_nlt_f32_e32 vcc, s6, v6
	s_mov_b32 s6, 0xc2b17218
	v_ldexp_f32 v2, v2, v3
	v_cndmask_b32_e32 v2, 0, v2, vcc
	v_cmp_ngt_f32_e32 vcc, s6, v6
	s_mov_b32 s6, 0x3f317217
	v_mul_f32_e32 v122, 0x3fb8aa3b, v6
	v_cndmask_b32_e32 v2, v208, v2, vcc
	v_sub_f32_e32 v2, 1.0, v2
	v_div_scale_f32 v3, s[8:9], v2, v2, 2.0
	v_rcp_f32_e32 v4, v3
	s_nop 0
	v_fma_f32 v5, -v3, v4, 1.0
	v_fmac_f32_e32 v4, v5, v4
	v_div_scale_f32 v5, vcc, 2.0, v2, 2.0
	v_mul_f32_e32 v7, v5, v4
	v_fma_f32 v8, -v3, v7, v5
	v_fmac_f32_e32 v7, v8, v4
	v_fma_f32 v3, -v3, v7, v5
	v_div_fmas_f32 v3, v3, v4, v7
	v_div_fixup_f32 v2, v3, v2, 2.0
	v_cmp_gt_f32_e32 vcc, s11, v2
	s_nop 1
	v_cndmask_b32_e64 v3, 0, 32, vcc
	v_ldexp_f32 v2, v2, v3
	v_log_f32_e32 v2, v2
	s_nop 0
	v_mul_f32_e32 v3, 0x3f317217, v2
	v_fma_f32 v3, v2, s6, -v3
	v_fmac_f32_e32 v3, 0x3377d1cf, v2
	s_mov_b32 s6, 0x7f800000
	v_fmac_f32_e32 v3, 0x3f317217, v2
	v_cmp_lt_f32_e64 s[8:9], |v2|, s6
	s_movk_i32 s6, 0x7f
	s_nop 0
	v_cndmask_b32_e64 v2, v2, v3, s[8:9]
	v_cndmask_b32_e32 v3, 0, v209, vcc
	v_sub_f32_e32 v2, v2, v3
	v_add_f32_e32 v2, v139, v2
	v_div_scale_f32 v3, s[8:9], v6, v6, v2
	v_rcp_f32_e32 v4, v3
	s_mov_b64 s[8:9], -1
	v_fma_f32 v5, -v3, v4, 1.0
	v_fmac_f32_e32 v4, v5, v4
	v_div_scale_f32 v5, vcc, v2, v6, v2
	v_mul_f32_e32 v7, v5, v4
	v_fma_f32 v8, -v3, v7, v5
	v_fmac_f32_e32 v7, v8, v4
	v_fma_f32 v3, -v3, v7, v5
	v_div_fmas_f32 v3, v3, v4, v7
	v_div_fixup_f32 v2, v3, v6, v2
	v_ceil_f32_e32 v2, v2
	v_cvt_i32_f32_e32 v2, v2
	v_sub_u32_e32 v3, v126, v2
	v_add3_u32 v2, v2, v126, s6
	v_max_i32_e32 v125, 0, v3
	v_min_i32_e32 v2, 0xfff, v2
	v_lshrrev_b32_e32 v141, 6, v125
	v_ashrrev_i32_e32 v155, 6, v2
	v_readfirstlane_b32 s6, v137
	s_cmp_gt_i32 s6, 3
	v_cmp_le_i32_e32 vcc, v141, v155
	s_cbranch_scc0 .LBB0_229
	s_waitcnt lgkmcnt(0)
	s_barrier
	v_mov_b32_e32 v65, 0
	v_mov_b32_e32 v64, v65
	v_mov_b32_e32 v63, v65
	v_mov_b32_e32 v62, v65
	v_mov_b32_e32 v61, v65
	v_mov_b32_e32 v60, v65
	v_mov_b32_e32 v59, v65
	v_mov_b32_e32 v58, v65
	v_mov_b32_e32 v57, v65
	v_mov_b32_e32 v56, v65
	v_mov_b32_e32 v55, v65
	v_mov_b32_e32 v54, v65
	v_mov_b32_e32 v53, v65
	v_mov_b32_e32 v52, v65
	v_mov_b32_e32 v51, v65
	v_mov_b32_e32 v50, v65
	v_mov_b32_e32 v49, v65
	v_mov_b32_e32 v48, v65
	v_mov_b32_e32 v47, v65
	v_mov_b32_e32 v46, v65
	v_mov_b32_e32 v45, v65
	v_mov_b32_e32 v44, v65
	v_mov_b32_e32 v43, v65
	v_mov_b32_e32 v42, v65
	v_mov_b32_e32 v41, v65
	v_mov_b32_e32 v40, v65
	v_mov_b32_e32 v39, v65
	v_mov_b32_e32 v38, v65
	v_mov_b32_e32 v37, v65
	v_mov_b32_e32 v36, v65
	v_mov_b32_e32 v35, v65
	v_mov_b32_e32 v34, v65
	v_mov_b32_e32 v33, v65
	v_mov_b32_e32 v32, v65
	v_mov_b32_e32 v31, v65
	v_mov_b32_e32 v30, v65
	v_mov_b32_e32 v29, v65
	v_mov_b32_e32 v28, v65
	v_mov_b32_e32 v27, v65
	v_mov_b32_e32 v26, v65
	v_mov_b32_e32 v25, v65
	v_mov_b32_e32 v24, v65
	v_mov_b32_e32 v23, v65
	v_mov_b32_e32 v22, v65
	v_mov_b32_e32 v21, v65
	v_mov_b32_e32 v20, v65
	v_mov_b32_e32 v19, v65
	v_mov_b32_e32 v18, v65
	v_mov_b32_e32 v17, v65
	v_mov_b32_e32 v16, v65
	v_mov_b32_e32 v15, v65
	v_mov_b32_e32 v14, v65
	v_mov_b32_e32 v13, v65
	v_mov_b32_e32 v12, v65
	v_mov_b32_e32 v11, v65
	v_mov_b32_e32 v10, v65
	v_mov_b32_e32 v9, v65
	v_mov_b32_e32 v8, v65
	v_mov_b32_e32 v7, v65
	v_mov_b32_e32 v6, v65
	v_mov_b32_e32 v5, v65
	v_mov_b32_e32 v4, v65
	v_mov_b32_e32 v3, v65
	v_mov_b32_e32 v2, v65
	v_mov_b32_e32 v160, v65
	s_and_saveexec_b64 s[8:9], vcc
	s_cbranch_execz .LBB0_228
	v_xor_b32_e32 v106, 0x80000000, v122
	v_lshl_or_b32 v2, v141, 6, v138
	v_mov_b32_e32 v160, 0
	v_sub_u32_e32 v127, v2, v66
	v_add_u32_e32 v128, -1, v141
	s_mov_b32 s33, 0
	s_mov_b64 s[84:85], 0
	v_mov_b32_e32 v2, 0
	v_mov_b32_e32 v3, v160
	v_mov_b32_e32 v4, v160
	v_mov_b32_e32 v5, v160
	v_mov_b32_e32 v6, v160
	v_mov_b32_e32 v7, v160
	v_mov_b32_e32 v8, v160
	v_mov_b32_e32 v9, v160
	v_mov_b32_e32 v10, v160
	v_mov_b32_e32 v11, v160
	v_mov_b32_e32 v12, v160
	v_mov_b32_e32 v13, v160
	v_mov_b32_e32 v14, v160
	v_mov_b32_e32 v15, v160
	v_mov_b32_e32 v16, v160
	v_mov_b32_e32 v17, v160
	v_mov_b32_e32 v18, 0
	v_mov_b32_e32 v19, v160
	v_mov_b32_e32 v20, v160
	v_mov_b32_e32 v21, v160
	v_mov_b32_e32 v22, v160
	v_mov_b32_e32 v23, v160
	v_mov_b32_e32 v24, v160
	v_mov_b32_e32 v25, v160
	v_mov_b32_e32 v26, v160
	v_mov_b32_e32 v27, v160
	v_mov_b32_e32 v28, v160
	v_mov_b32_e32 v29, v160
	v_mov_b32_e32 v30, v160
	v_mov_b32_e32 v31, v160
	v_mov_b32_e32 v32, v160
	v_mov_b32_e32 v33, v160
	v_mov_b32_e32 v34, 0
	v_mov_b32_e32 v35, v160
	v_mov_b32_e32 v36, v160
	v_mov_b32_e32 v37, v160
	v_mov_b32_e32 v38, v160
	v_mov_b32_e32 v39, v160
	v_mov_b32_e32 v40, v160
	v_mov_b32_e32 v41, v160
	v_mov_b32_e32 v42, v160
	v_mov_b32_e32 v43, v160
	v_mov_b32_e32 v44, v160
	v_mov_b32_e32 v45, v160
	v_mov_b32_e32 v46, v160
	v_mov_b32_e32 v47, v160
	v_mov_b32_e32 v48, v160
	v_mov_b32_e32 v49, v160
	v_mov_b32_e32 v50, 0
	v_mov_b32_e32 v51, v160
	v_mov_b32_e32 v52, v160
	v_mov_b32_e32 v53, v160
	v_mov_b32_e32 v54, v160
	v_mov_b32_e32 v55, v160
	v_mov_b32_e32 v56, v160
	v_mov_b32_e32 v57, v160
	v_mov_b32_e32 v58, v160
	v_mov_b32_e32 v59, v160
	v_mov_b32_e32 v60, v160
	v_mov_b32_e32 v61, v160
	v_mov_b32_e32 v62, v160
	v_mov_b32_e32 v63, v160
	v_mov_b32_e32 v64, v160
	v_mov_b32_e32 v65, v160
	v_cvt_f32_i32_e32 v162, v127
	v_add_f32_e32 v217, 1.0, v162
	v_add_f32_e32 v218, s12, v162
	v_add_f32_e32 v219, s13, v162
	v_add_f32_e32 v220, s16, v162
	v_add_f32_e32 v221, s17, v162
	v_add_f32_e32 v222, s18, v162
	v_add_f32_e32 v223, s19, v162
	v_add_f32_e32 v224, s20, v162
	v_add_f32_e32 v225, s21, v162
	v_add_f32_e32 v226, s22, v162
	v_add_f32_e32 v227, s23, v162
	v_add_f32_e32 v228, s26, v162
	v_add_f32_e32 v229, s27, v162
	v_add_f32_e32 v230, s28, v162
	v_add_f32_e32 v231, s29, v162
	v_fma_f32 v216, v106, |v162|, v146
	v_fma_f32 v217, v106, |v217|, v146
	v_fma_f32 v218, v106, |v218|, v146
	v_fma_f32 v219, v106, |v219|, v146
	v_fma_f32 v220, v106, |v220|, v146
	v_fma_f32 v221, v106, |v221|, v146
	v_fma_f32 v222, v106, |v222|, v146
	v_fma_f32 v223, v106, |v223|, v146
	v_fma_f32 v224, v106, |v224|, v146
	v_fma_f32 v225, v106, |v225|, v146
	v_fma_f32 v226, v106, |v226|, v146
	v_fma_f32 v227, v106, |v227|, v146
	v_fma_f32 v228, v106, |v228|, v146
	v_fma_f32 v229, v106, |v229|, v146
	v_fma_f32 v230, v106, |v230|, v146
	v_fma_f32 v231, v106, |v231|, v146
.LBB0_226:
	s_lshl_b32 s86, s33, 15
	v_or_b32_e32 v102, s86, v200
	s_waitcnt lgkmcnt(0)
	s_barrier
	v_add_u32_e32 v129, v102, v202
	ds_read_b128 v[98:101], v129
	v_add_u32_e32 v151, v102, v203
	v_add_f32_e32 v232, s74, v162
	v_add_f32_e32 v233, s75, v162
	v_add_f32_e32 v234, s64, v162
	v_add_f32_e32 v235, s65, v162
	v_add_f32_e32 v236, s58, v162
	v_add_f32_e32 v237, s59, v162
	v_add_f32_e32 v238, s56, v162
	v_add_f32_e32 v239, s57, v162
	s_waitcnt vmcnt(3) lgkmcnt(0)
	v_mfma_f32_32x32x16_bf16 v[216:231], v[98:101], v[82:85], v[216:231]
	ds_read_b128 v[98:101], v151
	v_add_u32_e32 v157, v102, v204
	v_add_u32_e32 v161, v102, v205
	s_add_i32 s6, s33, 1
	v_add_u32_e32 v128, 1, v128
	s_cmp_lg_u32 s33, 2
	v_cmp_ge_i32_e32 vcc, v128, v155
	v_add_f32_e32 v240, s54, v162
	v_add_f32_e32 v241, s55, v162
	v_add_f32_e32 v242, s48, v162
	v_add_f32_e32 v243, s49, v162
	s_waitcnt vmcnt(2) lgkmcnt(0)
	v_mfma_f32_32x32x16_bf16 v[216:231], v[98:101], v[86:89], v[216:231]
	ds_read_b128 v[98:101], v157
	s_cselect_b32 s33, s6, 0
	v_add_u32_e32 v127, 64, v127
	s_or_b64 s[84:85], vcc, s[84:85]
	v_add_f32_e32 v244, s34, v162
	v_add_f32_e32 v245, s35, v162
	v_add_f32_e32 v246, s30, v162
	v_add_f32_e32 v247, s31, v162
	v_fma_f32 v232, v106, |v232|, v146
	v_fma_f32 v233, v106, |v233|, v146
	s_waitcnt vmcnt(1) lgkmcnt(0)
	v_mfma_f32_32x32x16_bf16 v[216:231], v[98:101], v[90:93], v[216:231]
	ds_read_b128 v[98:101], v161
	v_fma_f32 v234, v106, |v234|, v146
	v_fma_f32 v235, v106, |v235|, v146
	v_fma_f32 v236, v106, |v236|, v146
	v_fma_f32 v237, v106, |v237|, v146
	v_fma_f32 v238, v106, |v238|, v146
	v_fma_f32 v239, v106, |v239|, v146
	s_waitcnt vmcnt(0) lgkmcnt(0)
	v_mfma_f32_32x32x16_bf16 v[216:231], v[98:101], v[94:97], v[216:231]
	ds_read_b128 v[162:165], v129 offset:8192
	v_fma_f32 v240, v106, |v240|, v146
	v_fma_f32 v241, v106, |v241|, v146
	v_fma_f32 v242, v106, |v242|, v146
	v_fma_f32 v243, v106, |v243|, v146
	v_fma_f32 v244, v106, |v244|, v146
	v_fma_f32 v245, v106, |v245|, v146
	v_fma_f32 v246, v106, |v246|, v146
	v_fma_f32 v247, v106, |v247|, v146
	s_nop 2
	v_exp_f32_e32 v66, v216
	v_exp_f32_e32 v166, v217
	v_exp_f32_e32 v168, v218
	v_exp_f32_e32 v170, v219
	v_add_f32_e32 v132, 0, v66
	s_waitcnt lgkmcnt(0)
	v_mfma_f32_32x32x16_bf16 v[232:247], v[162:165], v[82:85], v[232:247]
	ds_read_b128 v[162:165], v151 offset:8192
	v_exp_f32_e32 v188, v228
	v_exp_f32_e32 v212, v229
	v_exp_f32_e32 v214, v230
	v_exp_f32_e32 v250, v231
	v_cvt_pk_bf16_f32 v98, v66, v166
	s_waitcnt lgkmcnt(0)
	v_mfma_f32_32x32x16_bf16 v[232:247], v[162:165], v[86:89], v[232:247]
	ds_read_b128 v[162:165], v157 offset:8192
	v_exp_f32_e32 v172, v220
	v_exp_f32_e32 v174, v221
	v_exp_f32_e32 v176, v222
	v_exp_f32_e32 v178, v223
	s_waitcnt lgkmcnt(0)
	v_mfma_f32_32x32x16_bf16 v[232:247], v[162:165], v[90:93], v[232:247]
	ds_read_b128 v[162:165], v161 offset:8192
	v_exp_f32_e32 v180, v224
	v_exp_f32_e32 v182, v225
	v_exp_f32_e32 v184, v226
	v_exp_f32_e32 v186, v227
	s_waitcnt lgkmcnt(0)
	s_barrier
	s_waitcnt lgkmcnt(0)
	v_mfma_f32_32x32x16_bf16 v[232:247], v[162:165], v[94:97], v[232:247]
	v_cvt_pk_bf16_f32 v99, v168, v170
	v_cvt_pk_bf16_f32 v100, v172, v174
	v_cvt_pk_bf16_f32 v101, v176, v178
	v_cvt_pk_bf16_f32 v102, v180, v182
	v_cvt_pk_bf16_f32 v103, v184, v186
	v_cvt_pk_bf16_f32 v104, v188, v212
	v_cvt_pk_bf16_f32 v105, v214, v250
	v_or_b32_e32 v80, s86, v193
	v_add_u32_e32 v81, v80, v195
	ds_read_b128 v[74:77], v81 offset:16384
	v_add_u32_e32 v129, v80, v196
	s_nop 0
	v_exp_f32_e32 v251, v246
	v_exp_f32_e32 v161, v247
	v_exp_f32_e32 v183, v240
	v_exp_f32_e32 v185, v241
	v_exp_f32_e32 v187, v242
	v_exp_f32_e32 v189, v243
	s_waitcnt lgkmcnt(0)
	v_mfma_f32_32x32x16_bf16 v[50:65], v[74:77], v[98:101], v[50:65]
	ds_read_b128 v[74:77], v129 offset:16384
	v_exp_f32_e32 v167, v232
	v_exp_f32_e32 v169, v233
	v_exp_f32_e32 v171, v234
	v_exp_f32_e32 v173, v235
	v_pk_add_f32 v[66:67], v[166:167], v[132:133]
	v_exp_f32_e32 v175, v236
	s_waitcnt lgkmcnt(0)
	v_mfma_f32_32x32x16_bf16 v[50:65], v[74:77], v[102:105], v[50:65]
	ds_read_b128 v[74:77], v81 offset:20480
	v_add_f32_e64 v66, v168, v66
	v_add_f32_e64 v67, v169, v67
	v_exp_f32_e32 v177, v237
	v_pk_add_f32 v[66:67], v[170:171], v[66:67]
	v_exp_f32_e32 v179, v238
	v_pk_add_f32 v[66:67], v[172:173], v[66:67]
	v_exp_f32_e32 v181, v239
	s_waitcnt lgkmcnt(0)
	v_mfma_f32_32x32x16_bf16 v[34:49], v[74:77], v[98:101], v[34:49]
	ds_read_b128 v[74:77], v129 offset:20480
	v_add_f32_e64 v66, v174, v66
	v_add_f32_e64 v67, v175, v67
	v_exp_f32_e32 v213, v244
	v_pk_add_f32 v[66:67], v[176:177], v[66:67]
	v_exp_f32_e32 v215, v245
	v_pk_add_f32 v[66:67], v[178:179], v[66:67]
	v_cvt_pk_bf16_f32 v68, v175, v177
	s_waitcnt lgkmcnt(0)
	v_mfma_f32_32x32x16_bf16 v[34:49], v[74:77], v[102:105], v[34:49]
	ds_read_b128 v[74:77], v81 offset:24576
	v_add_f32_e64 v66, v180, v66
	v_add_f32_e64 v67, v181, v67
	v_cvt_pk_bf16_f32 v69, v179, v181
	v_add_f32_e64 v66, v182, v66
	v_add_f32_e64 v67, v183, v67
	v_cvt_pk_bf16_f32 v70, v183, v185
	v_pk_add_f32 v[66:67], v[184:185], v[66:67]
	v_cvt_pk_bf16_f32 v71, v187, v189
	s_waitcnt lgkmcnt(0)
	v_mfma_f32_32x32x16_bf16 v[18:33], v[74:77], v[98:101], v[18:33]
	ds_read_b128 v[74:77], v129 offset:24576
	v_add_f32_e64 v66, v186, v66
	v_add_f32_e64 v67, v187, v67
	v_cvt_pk_bf16_f32 v72, v213, v215
	v_add_f32_e64 v66, v188, v66
	v_add_f32_e64 v67, v189, v67
	v_cvt_pk_bf16_f32 v73, v251, v161
	v_pk_add_f32 v[66:67], v[212:213], v[66:67]
	s_waitcnt lgkmcnt(0)
	v_mfma_f32_32x32x16_bf16 v[18:33], v[74:77], v[102:105], v[18:33]
	ds_read_b128 v[74:77], v81 offset:28672
	v_add_u32_e32 v81, v80, v197
	v_add_f32_e64 v66, v214, v66
	v_add_f32_e64 v67, v215, v67
	v_add_u32_e32 v80, v80, v198
	v_pk_add_f32 v[66:67], v[250:251], v[66:67]
	s_nop 0
	v_pk_add_f32 v[78:79], v[160:161], v[66:67]
	s_waitcnt lgkmcnt(0)
	v_mfma_f32_32x32x16_bf16 v[2:17], v[74:77], v[98:101], v[2:17]
	ds_read_b128 v[74:77], v129 offset:28672
	v_cvt_pk_bf16_f32 v66, v167, v169
	v_cvt_pk_bf16_f32 v67, v171, v173
	v_add_f32_e32 v160, v78, v79
	s_waitcnt lgkmcnt(0)
	v_mfma_f32_32x32x16_bf16 v[2:17], v[74:77], v[102:105], v[2:17]
	ds_read_b128 v[74:77], v81 offset:16384
	v_cvt_f32_i32_e32 v162, v127
	v_add_f32_e32 v217, 1.0, v162
	v_add_f32_e32 v218, s12, v162
	v_add_f32_e32 v219, s13, v162
	s_waitcnt lgkmcnt(0)
	v_mfma_f32_32x32x16_bf16 v[50:65], v[74:77], v[66:69], v[50:65]
	ds_read_b128 v[74:77], v80 offset:16384
	v_add_f32_e32 v220, s16, v162
	v_add_f32_e32 v221, s17, v162
	v_add_f32_e32 v222, s18, v162
	v_add_f32_e32 v223, s19, v162
	s_waitcnt lgkmcnt(0)
	v_mfma_f32_32x32x16_bf16 v[50:65], v[74:77], v[70:73], v[50:65]
	ds_read_b128 v[74:77], v81 offset:20480
	v_add_f32_e32 v224, s20, v162
	v_add_f32_e32 v225, s21, v162
	v_add_f32_e32 v226, s22, v162
	v_add_f32_e32 v227, s23, v162
	s_waitcnt lgkmcnt(0)
	v_mfma_f32_32x32x16_bf16 v[34:49], v[74:77], v[66:69], v[34:49]
	ds_read_b128 v[74:77], v80 offset:20480
	v_add_f32_e32 v228, s26, v162
	v_add_f32_e32 v229, s27, v162
	v_add_f32_e32 v230, s28, v162
	v_add_f32_e32 v231, s29, v162
	s_waitcnt lgkmcnt(0)
	v_mfma_f32_32x32x16_bf16 v[34:49], v[74:77], v[70:73], v[34:49]
	ds_read_b128 v[74:77], v81 offset:24576
	v_fma_f32 v216, v106, |v162|, v146
	v_fma_f32 v217, v106, |v217|, v146
	v_fma_f32 v218, v106, |v218|, v146
	v_fma_f32 v219, v106, |v219|, v146
	s_waitcnt lgkmcnt(0)
	v_mfma_f32_32x32x16_bf16 v[18:33], v[74:77], v[66:69], v[18:33]
	ds_read_b128 v[74:77], v80 offset:24576
	v_fma_f32 v220, v106, |v220|, v146
	v_fma_f32 v221, v106, |v221|, v146
	v_fma_f32 v222, v106, |v222|, v146
	v_fma_f32 v223, v106, |v223|, v146
	s_waitcnt lgkmcnt(0)
	v_mfma_f32_32x32x16_bf16 v[18:33], v[74:77], v[70:73], v[18:33]
	ds_read_b128 v[74:77], v81 offset:28672
	v_fma_f32 v224, v106, |v224|, v146
	v_fma_f32 v225, v106, |v225|, v146
	v_fma_f32 v226, v106, |v226|, v146
	v_fma_f32 v227, v106, |v227|, v146
	s_waitcnt lgkmcnt(0)
	v_mfma_f32_32x32x16_bf16 v[2:17], v[74:77], v[66:69], v[2:17]
	ds_read_b128 v[66:69], v80 offset:28672
	v_fma_f32 v228, v106, |v228|, v146
	v_fma_f32 v229, v106, |v229|, v146
	v_fma_f32 v230, v106, |v230|, v146
	v_fma_f32 v231, v106, |v231|, v146
	s_waitcnt lgkmcnt(0)
	v_mfma_f32_32x32x16_bf16 v[2:17], v[66:69], v[70:73], v[2:17]
	s_andn2_b64 exec, exec, s[84:85]
	s_cbranch_execnz .LBB0_226
	s_or_b64 exec, exec, s[84:85]

.LBB0_230:
	s_nop 5
	v_or_b32_e32 v2, v124, v1
	v_lshlrev_b32_e32 v132, 11, v2
	v_lshl_add_u64 v[2:3], s[72:73], 0, v[132:133]
	v_lshl_add_u64 v[2:3], v[158:159], 1, v[2:3]
	v_mov_b32_e32 v151, v133
	v_lshl_add_u64 v[106:107], v[2:3], 0, v[150:151]
	v_lshl_add_u32 v2, v123, 10, v158
	v_or_b32_e32 v132, v2, v190
	v_lshlrev_b64 v[2:3], 13, v[132:133]
	v_and_b32_e32 v132, 0x7fffffc0, v125
	v_lshlrev_b64 v[4:5], 11, v[132:133]
	v_readfirstlane_b32 s6, v191
	v_lshl_add_u64 v[4:5], v[106:107], 0, v[4:5]
	s_mov_b32 m0, s6
	v_lshl_add_u64 v[108:109], v[142:143], 0, v[2:3]
	global_load_lds_dwordx4 v[4:5], off
	v_or_b32_e32 v4, 0x4000, v191
	v_lshlrev_b32_e32 v2, 1, v132
	v_mov_b32_e32 v3, v133
	v_readfirstlane_b32 s6, v4
	v_or_b32_e32 v4, 16, v132
	v_mov_b32_e32 v5, v133
	v_add_u32_e32 v6, 0x1000, v191
	v_lshl_add_u64 v[2:3], v[108:109], 0, v[2:3]
	s_mov_b32 m0, s6
	v_lshlrev_b64 v[4:5], 11, v[4:5]
	v_readfirstlane_b32 s6, v6
	v_add_u32_e32 v6, 0x5000, v191
	global_load_lds_dwordx4 v[2:3], off
	v_lshl_add_u64 v[4:5], v[106:107], 0, v[4:5]
	s_mov_b32 m0, s6
	v_readfirstlane_b32 s6, v6
	global_load_lds_dwordx4 v[4:5], off
	v_lshl_add_u64 v[4:5], v[2:3], 0, s[88:89]
	s_mov_b32 m0, s6
	v_or_b32_e32 v6, 0x2000, v191
	global_load_lds_dwordx4 v[4:5], off
	v_or_b32_e32 v4, 32, v132
	v_mov_b32_e32 v5, v133
	v_lshlrev_b64 v[4:5], 11, v[4:5]
	v_readfirstlane_b32 s6, v6
	v_or_b32_e32 v6, 0x6000, v191
	v_lshl_add_u64 v[4:5], v[106:107], 0, v[4:5]
	s_mov_b32 m0, s6
	v_readfirstlane_b32 s6, v6
	global_load_lds_dwordx4 v[4:5], off
	v_lshl_add_u64 v[4:5], v[2:3], 0, s[92:93]
	s_mov_b32 m0, s6
	v_or_b32_e32 v132, 48, v132
	v_add_u32_e32 v6, 0x3000, v191
	global_load_lds_dwordx4 v[4:5], off
	v_lshlrev_b64 v[4:5], 11, v[132:133]
	v_readfirstlane_b32 s6, v6
	v_lshl_add_u64 v[4:5], v[106:107], 0, v[4:5]
	s_mov_b32 m0, s6
	v_lshl_add_u64 v[2:3], v[2:3], 0, s[94:95]
	global_load_lds_dwordx4 v[4:5], off
	v_add_u32_e32 v4, 0x7000, v191
	v_mov_b32_e32 v65, 0
	v_readfirstlane_b32 s6, v4
	s_mov_b32 m0, s6
	v_cmp_le_i32_e32 vcc, v141, v155
	global_load_lds_dwordx4 v[2:3], off
	v_mov_b32_e32 v64, v65
	v_mov_b32_e32 v63, v65
	v_mov_b32_e32 v62, v65
	v_mov_b32_e32 v61, v65
	v_mov_b32_e32 v60, v65
	v_mov_b32_e32 v59, v65
	v_mov_b32_e32 v58, v65
	v_mov_b32_e32 v57, v65
	v_mov_b32_e32 v56, v65
	v_mov_b32_e32 v55, v65
	v_mov_b32_e32 v54, v65
	v_mov_b32_e32 v53, v65
	v_mov_b32_e32 v52, v65
	v_mov_b32_e32 v51, v65
	v_mov_b32_e32 v50, v65
	v_mov_b32_e32 v49, v65
	v_mov_b32_e32 v48, v65
	v_mov_b32_e32 v47, v65
	v_mov_b32_e32 v46, v65
	v_mov_b32_e32 v45, v65
	v_mov_b32_e32 v44, v65
	v_mov_b32_e32 v43, v65
	v_mov_b32_e32 v42, v65
	v_mov_b32_e32 v41, v65
	v_mov_b32_e32 v40, v65
	v_mov_b32_e32 v39, v65
	v_mov_b32_e32 v38, v65
	v_mov_b32_e32 v37, v65
	v_mov_b32_e32 v36, v65
	v_mov_b32_e32 v35, v65
	v_mov_b32_e32 v34, v65
	v_mov_b32_e32 v33, v65
	v_mov_b32_e32 v32, v65
	v_mov_b32_e32 v31, v65
	v_mov_b32_e32 v30, v65
	v_mov_b32_e32 v29, v65
	v_mov_b32_e32 v28, v65
	v_mov_b32_e32 v27, v65
	v_mov_b32_e32 v26, v65
	v_mov_b32_e32 v25, v65
	v_mov_b32_e32 v24, v65
	v_mov_b32_e32 v23, v65
	v_mov_b32_e32 v22, v65
	v_mov_b32_e32 v21, v65
	v_mov_b32_e32 v20, v65
	v_mov_b32_e32 v19, v65
	v_mov_b32_e32 v18, v65
	v_mov_b32_e32 v17, v65
	v_mov_b32_e32 v16, v65
	v_mov_b32_e32 v15, v65
	v_mov_b32_e32 v14, v65
	v_mov_b32_e32 v13, v65
	v_mov_b32_e32 v12, v65
	v_mov_b32_e32 v11, v65
	v_mov_b32_e32 v10, v65
	v_mov_b32_e32 v9, v65
	v_mov_b32_e32 v8, v65
	v_mov_b32_e32 v7, v65
	v_mov_b32_e32 v6, v65
	v_mov_b32_e32 v5, v65
	v_mov_b32_e32 v4, v65
	v_mov_b32_e32 v3, v65
	v_mov_b32_e32 v2, v65
	v_mov_b32_e32 v160, v65
	s_and_saveexec_b64 s[8:9], vcc
	s_cbranch_execz .LBB0_238
	v_xor_b32_e32 v110, 0x80000000, v122
	v_mov_b32_e32 v160, 0
	v_mov_b32_e32 v111, v110
	v_mov_b32_e32 v112, v110
	v_mov_b32_e32 v113, v110
	v_mov_b32_e32 v114, v110
	v_mov_b32_e32 v115, v110
	v_mov_b32_e32 v116, v110
	v_mov_b32_e32 v117, v110
	v_mov_b32_e32 v118, v110
	v_mov_b32_e32 v119, v110
	v_mov_b32_e32 v120, v110
	v_mov_b32_e32 v121, v110
	v_mov_b32_e32 v122, v110
	v_mov_b32_e32 v123, v110
	v_mov_b32_e32 v124, v110
	v_mov_b32_e32 v125, v110
	v_lshlrev_b32_e32 v66, 6, v141
	v_sub_u32_e32 v151, v201, v126
	s_mov_b32 s90, 0
	s_mov_b64 s[84:85], 0
	v_mov_b32_e32 v2, 0
	v_mov_b32_e32 v3, v160
	v_mov_b32_e32 v4, v160
	v_mov_b32_e32 v5, v160
	v_mov_b32_e32 v6, v160
	v_mov_b32_e32 v7, v160
	v_mov_b32_e32 v8, v160
	v_mov_b32_e32 v9, v160
	v_mov_b32_e32 v10, v160
	v_mov_b32_e32 v11, v160
	v_mov_b32_e32 v12, v160
	v_mov_b32_e32 v13, v160
	v_mov_b32_e32 v14, v160
	v_mov_b32_e32 v15, v160
	v_mov_b32_e32 v16, v160
	v_mov_b32_e32 v17, v160
	v_mov_b32_e32 v18, 0
	v_mov_b32_e32 v19, v160
	v_mov_b32_e32 v20, v160
	v_mov_b32_e32 v21, v160
	v_mov_b32_e32 v22, v160
	v_mov_b32_e32 v23, v160
	v_mov_b32_e32 v24, v160
	v_mov_b32_e32 v25, v160
	v_mov_b32_e32 v26, v160
	v_mov_b32_e32 v27, v160
	v_mov_b32_e32 v28, v160
	v_mov_b32_e32 v29, v160
	v_mov_b32_e32 v30, v160
	v_mov_b32_e32 v31, v160
	v_mov_b32_e32 v32, v160
	v_mov_b32_e32 v33, v160
	v_mov_b32_e32 v34, 0
	v_mov_b32_e32 v35, v160
	v_mov_b32_e32 v36, v160
	v_mov_b32_e32 v37, v160
	v_mov_b32_e32 v38, v160
	v_mov_b32_e32 v39, v160
	v_mov_b32_e32 v40, v160
	v_mov_b32_e32 v41, v160
	v_mov_b32_e32 v42, v160
	v_mov_b32_e32 v43, v160
	v_mov_b32_e32 v44, v160
	v_mov_b32_e32 v45, v160
	v_mov_b32_e32 v46, v160
	v_mov_b32_e32 v47, v160
	v_mov_b32_e32 v48, v160
	v_mov_b32_e32 v49, v160
	v_mov_b32_e32 v50, 0
	v_mov_b32_e32 v51, v160
	v_mov_b32_e32 v52, v160
	v_mov_b32_e32 v53, v160
	v_mov_b32_e32 v54, v160
	v_mov_b32_e32 v55, v160
	v_mov_b32_e32 v56, v160
	v_mov_b32_e32 v57, v160
	v_mov_b32_e32 v58, v160
	v_mov_b32_e32 v59, v160
	v_mov_b32_e32 v60, v160
	v_mov_b32_e32 v61, v160
	v_mov_b32_e32 v62, v160
	v_mov_b32_e32 v63, v160
	v_mov_b32_e32 v64, v160
	v_mov_b32_e32 v65, v160
	v_add_u32_e32 v250, v151, v66
	v_cvt_f32_i32_e32 v212, v250
	v_add_f32_e32 v217, 1.0, v212
	v_add_f32_e32 v218, s12, v212
	v_add_f32_e32 v219, s13, v212
	v_add_f32_e32 v220, s16, v212
	v_add_f32_e32 v221, s17, v212
	v_add_f32_e32 v222, s18, v212
	v_add_f32_e32 v223, s19, v212
	v_add_f32_e32 v224, s20, v212
	v_add_f32_e32 v225, s21, v212
	v_add_f32_e32 v226, s22, v212
	v_add_f32_e32 v227, s23, v212
	v_add_f32_e32 v228, s26, v212
	v_add_f32_e32 v229, s27, v212
	v_add_f32_e32 v230, s28, v212
	v_add_f32_e32 v231, s29, v212
	v_fma_f32 v216, v110, |v212|, v146
	v_fma_f32 v217, v110, |v217|, v146
	v_fma_f32 v218, v110, |v218|, v146
	v_fma_f32 v219, v110, |v219|, v146
	v_fma_f32 v220, v110, |v220|, v146
	v_fma_f32 v221, v110, |v221|, v146
	v_fma_f32 v222, v110, |v222|, v146
	v_fma_f32 v223, v110, |v223|, v146
	v_fma_f32 v224, v110, |v224|, v146
	v_fma_f32 v225, v110, |v225|, v146
	v_fma_f32 v226, v110, |v226|, v146
	v_fma_f32 v227, v110, |v227|, v146
	v_fma_f32 v228, v110, |v228|, v146
	v_fma_f32 v229, v110, |v229|, v146
	v_fma_f32 v230, v110, |v230|, v146
	v_fma_f32 v231, v110, |v231|, v146
	s_waitcnt vmcnt(0)
	s_branch .LBB0_233
.LBB0_232:
	s_or_b64 exec, exec, s[86:87]
	s_and_b64 s[6:7], exec, vcc
	s_or_b64 s[84:85], s[6:7], s[84:85]
	s_lshl_b32 s86, s90, 15
	v_or_b32_e32 v102, s86, v200
	v_add_u32_e32 v127, v102, v202
	ds_read_b128 v[98:101], v127
	v_add_u32_e32 v129, v102, v203
	v_add_f32_e32 v232, s74, v212
	v_add_f32_e32 v233, s75, v212
	v_add_f32_e32 v234, s64, v212
	v_add_f32_e32 v235, s65, v212
	v_add_f32_e32 v236, s58, v212
	v_add_f32_e32 v237, s59, v212
	v_add_f32_e32 v238, s56, v212
	v_add_f32_e32 v239, s57, v212
	s_waitcnt lgkmcnt(0)
	v_mfma_f32_32x32x16_bf16 v[216:231], v[98:101], v[82:85], v[216:231]
	ds_read_b128 v[98:101], v129
	v_add_u32_e32 v157, v102, v204
	v_add_u32_e32 v161, v102, v205
	v_add_u32_e32 v141, 1, v141
	s_mov_b32 s90, s33
	v_add_f32_e32 v240, s54, v212
	v_add_f32_e32 v241, s55, v212
	v_add_f32_e32 v242, s48, v212
	v_add_f32_e32 v243, s49, v212
	s_waitcnt lgkmcnt(0)
	v_mfma_f32_32x32x16_bf16 v[216:231], v[98:101], v[86:89], v[216:231]
	ds_read_b128 v[98:101], v157
	v_add_f32_e32 v244, s34, v212
	v_add_f32_e32 v245, s35, v212
	v_add_f32_e32 v246, s30, v212
	v_add_f32_e32 v247, s31, v212
	v_fma_f32 v232, v110, |v232|, v146
	v_fma_f32 v233, v110, |v233|, v146
	s_waitcnt lgkmcnt(0)
	v_mfma_f32_32x32x16_bf16 v[216:231], v[98:101], v[90:93], v[216:231]
	ds_read_b128 v[98:101], v161
	v_fma_f32 v234, v110, |v234|, v146
	v_fma_f32 v235, v110, |v235|, v146
	v_fma_f32 v236, v110, |v236|, v146
	v_fma_f32 v237, v110, |v237|, v146
	v_fma_f32 v238, v110, |v238|, v146
	v_fma_f32 v239, v110, |v239|, v146
	s_waitcnt lgkmcnt(0)
	v_mfma_f32_32x32x16_bf16 v[216:231], v[98:101], v[94:97], v[216:231]
	ds_read_b128 v[212:215], v127 offset:8192
	v_fma_f32 v240, v110, |v240|, v146
	v_fma_f32 v241, v110, |v241|, v146
	v_fma_f32 v242, v110, |v242|, v146
	v_fma_f32 v243, v110, |v243|, v146
	v_fma_f32 v244, v110, |v244|, v146
	v_fma_f32 v245, v110, |v245|, v146
	v_fma_f32 v246, v110, |v246|, v146
	v_fma_f32 v247, v110, |v247|, v146
	s_nop 2
	v_exp_f32_e32 v66, v216
	v_exp_f32_e32 v128, v217
	v_exp_f32_e32 v164, v218
	v_exp_f32_e32 v162, v219
	v_add_f32_e32 v132, 0, v66
	s_waitcnt lgkmcnt(0)
	v_mfma_f32_32x32x16_bf16 v[232:247], v[212:215], v[82:85], v[232:247]
	ds_read_b128 v[212:215], v129 offset:8192
	v_exp_f32_e32 v184, v228
	v_exp_f32_e32 v182, v229
	v_exp_f32_e32 v188, v230
	v_exp_f32_e32 v186, v231
	v_cvt_pk_bf16_f32 v102, v66, v128
	s_waitcnt lgkmcnt(0)
	v_mfma_f32_32x32x16_bf16 v[232:247], v[212:215], v[86:89], v[232:247]
	ds_read_b128 v[212:215], v157 offset:8192
	v_exp_f32_e32 v168, v220
	v_exp_f32_e32 v166, v221
	v_exp_f32_e32 v172, v222
	v_exp_f32_e32 v170, v223
	s_waitcnt lgkmcnt(0)
	v_mfma_f32_32x32x16_bf16 v[232:247], v[212:215], v[90:93], v[232:247]
	ds_read_b128 v[212:215], v161 offset:8192
	v_exp_f32_e32 v176, v224
	v_exp_f32_e32 v174, v225
	v_exp_f32_e32 v180, v226
	v_exp_f32_e32 v178, v227
	s_waitcnt lgkmcnt(0)
	s_barrier
	s_waitcnt lgkmcnt(0)
	v_mfma_f32_32x32x16_bf16 v[232:247], v[212:215], v[94:97], v[232:247]
	v_cvt_pk_bf16_f32 v103, v164, v162
	v_cvt_pk_bf16_f32 v104, v168, v166
	v_cvt_pk_bf16_f32 v105, v172, v170
	v_cvt_pk_bf16_f32 v98, v176, v174
	v_cvt_pk_bf16_f32 v99, v180, v178
	v_cvt_pk_bf16_f32 v100, v184, v182
	v_cvt_pk_bf16_f32 v101, v188, v186
	v_or_b32_e32 v80, s86, v193
	v_add_u32_e32 v81, v80, v195
	ds_read_b128 v[76:79], v81 offset:16384
	v_add_u32_e32 v127, v80, v196
	s_nop 0
	v_exp_f32_e32 v187, v246
	v_exp_f32_e32 v161, v247
	v_exp_f32_e32 v179, v242
	v_exp_f32_e32 v185, v243
	v_exp_f32_e32 v183, v244
	v_exp_f32_e32 v189, v245
	s_waitcnt lgkmcnt(0)
	v_mfma_f32_32x32x16_bf16 v[50:65], v[76:79], v[102:105], v[50:65]
	ds_read_b128 v[76:79], v127 offset:16384
	v_exp_f32_e32 v129, v232
	v_exp_f32_e32 v165, v233
	v_exp_f32_e32 v163, v234
	v_exp_f32_e32 v169, v235
	v_pk_add_f32 v[66:67], v[128:129], v[132:133]
	v_exp_f32_e32 v167, v236
	s_waitcnt lgkmcnt(0)
	v_mfma_f32_32x32x16_bf16 v[50:65], v[76:79], v[98:101], v[50:65]
	ds_read_b128 v[76:79], v81 offset:20480
	v_add_f32_e64 v66, v164, v66
	v_add_f32_e64 v67, v165, v67
	v_exp_f32_e32 v173, v237
	v_pk_add_f32 v[66:67], v[162:163], v[66:67]
	v_exp_f32_e32 v171, v238
	v_exp_f32_e32 v177, v239
	v_pk_add_f32 v[66:67], v[168:169], v[66:67]
	s_waitcnt lgkmcnt(0)
	v_mfma_f32_32x32x16_bf16 v[34:49], v[76:79], v[102:105], v[34:49]
	ds_read_b128 v[76:79], v127 offset:20480
	v_exp_f32_e32 v175, v240
	v_pk_add_f32 v[66:67], v[166:167], v[66:67]
	v_exp_f32_e32 v181, v241
	v_pk_add_f32 v[66:67], v[172:173], v[66:67]
	v_cvt_pk_bf16_f32 v70, v129, v165
	v_pk_add_f32 v[66:67], v[170:171], v[66:67]
	s_waitcnt lgkmcnt(0)
	v_mfma_f32_32x32x16_bf16 v[34:49], v[76:79], v[98:101], v[34:49]
	ds_read_b128 v[76:79], v81 offset:24576
	v_cvt_pk_bf16_f32 v71, v163, v169
	v_cvt_pk_bf16_f32 v72, v167, v173
	v_cvt_pk_bf16_f32 v73, v171, v177
	v_add_f32_e64 v66, v176, v66
	v_add_f32_e64 v67, v177, v67
	v_cvt_pk_bf16_f32 v68, v183, v189
	v_pk_add_f32 v[66:67], v[174:175], v[66:67]
	s_waitcnt lgkmcnt(0)
	v_mfma_f32_32x32x16_bf16 v[18:33], v[76:79], v[102:105], v[18:33]
	ds_read_b128 v[76:79], v127 offset:24576
	v_add_f32_e64 v66, v180, v66
	v_add_f32_e64 v67, v181, v67
	v_cvt_pk_bf16_f32 v69, v187, v161
	v_add_f32_e64 v66, v178, v66
	v_add_f32_e64 v67, v179, v67
	v_pk_add_f32 v[66:67], v[184:185], v[66:67]
	s_waitcnt lgkmcnt(0)
	v_mfma_f32_32x32x16_bf16 v[18:33], v[76:79], v[98:101], v[18:33]
	ds_read_b128 v[76:79], v81 offset:28672
	v_add_u32_e32 v81, v80, v197
	v_add_u32_e32 v80, v80, v198
	v_add_f32_e64 v66, v182, v66
	v_add_f32_e64 v67, v183, v67
	v_pk_add_f32 v[66:67], v[188:189], v[66:67]
	s_waitcnt lgkmcnt(0)
	v_mfma_f32_32x32x16_bf16 v[2:17], v[76:79], v[102:105], v[2:17]
	ds_read_b128 v[76:79], v127 offset:28672
	v_add_f32_e64 v66, v186, v66
	v_add_f32_e64 v67, v187, v67
	v_add_f32_e64 v74, v160, v66
	v_add_f32_e64 v75, v161, v67
	v_cvt_pk_bf16_f32 v66, v175, v181
	v_cvt_pk_bf16_f32 v67, v179, v185
	v_add_f32_e32 v160, v74, v75
	s_waitcnt lgkmcnt(0)
	v_mfma_f32_32x32x16_bf16 v[2:17], v[76:79], v[98:101], v[2:17]
	ds_read_b128 v[76:79], v81 offset:16384
	v_add_u32_e32 v250, v151, v126
	v_cvt_f32_i32_e32 v212, v250
	v_add_f32_e32 v217, 1.0, v212
	v_add_f32_e32 v218, s12, v212
	v_add_f32_e32 v219, s13, v212
	s_waitcnt lgkmcnt(0)
	v_mfma_f32_32x32x16_bf16 v[50:65], v[76:79], v[70:73], v[50:65]
	ds_read_b128 v[76:79], v80 offset:16384
	v_add_f32_e32 v220, s16, v212
	v_add_f32_e32 v221, s17, v212
	v_add_f32_e32 v222, s18, v212
	v_add_f32_e32 v223, s19, v212
	s_waitcnt lgkmcnt(0)
	v_mfma_f32_32x32x16_bf16 v[50:65], v[76:79], v[66:69], v[50:65]
	ds_read_b128 v[76:79], v81 offset:20480
	v_add_f32_e32 v224, s20, v212
	v_add_f32_e32 v225, s21, v212
	v_add_f32_e32 v226, s22, v212
	v_add_f32_e32 v227, s23, v212
	s_waitcnt lgkmcnt(0)
	v_mfma_f32_32x32x16_bf16 v[34:49], v[76:79], v[70:73], v[34:49]
	ds_read_b128 v[76:79], v80 offset:20480
	v_add_f32_e32 v228, s26, v212
	v_add_f32_e32 v229, s27, v212
	v_add_f32_e32 v230, s28, v212
	v_add_f32_e32 v231, s29, v212
	s_waitcnt lgkmcnt(0)
	v_mfma_f32_32x32x16_bf16 v[34:49], v[76:79], v[66:69], v[34:49]
	ds_read_b128 v[76:79], v81 offset:24576
	v_fma_f32 v216, v110, |v212|, v146
	v_fma_f32 v217, v110, |v217|, v146
	v_fma_f32 v218, v110, |v218|, v146
	v_fma_f32 v219, v110, |v219|, v146
	s_waitcnt lgkmcnt(0)
	v_mfma_f32_32x32x16_bf16 v[18:33], v[76:79], v[70:73], v[18:33]
	ds_read_b128 v[76:79], v80 offset:24576
	v_fma_f32 v220, v110, |v220|, v146
	v_fma_f32 v221, v110, |v221|, v146
	v_fma_f32 v222, v110, |v222|, v146
	v_fma_f32 v223, v110, |v223|, v146
	s_waitcnt lgkmcnt(0)
	v_mfma_f32_32x32x16_bf16 v[18:33], v[76:79], v[66:69], v[18:33]
	ds_read_b128 v[76:79], v81 offset:28672
	v_fma_f32 v224, v110, |v224|, v146
	v_fma_f32 v225, v110, |v225|, v146
	v_fma_f32 v226, v110, |v226|, v146
	v_fma_f32 v227, v110, |v227|, v146
	s_waitcnt lgkmcnt(0)
	v_mfma_f32_32x32x16_bf16 v[2:17], v[76:79], v[70:73], v[2:17]
	ds_read_b128 v[70:73], v80 offset:28672
	v_fma_f32 v228, v110, |v228|, v146
	v_fma_f32 v229, v110, |v229|, v146
	v_fma_f32 v230, v110, |v230|, v146
	v_fma_f32 v231, v110, |v231|, v146
	s_waitcnt lgkmcnt(0)
	v_mfma_f32_32x32x16_bf16 v[2:17], v[70:73], v[66:69], v[2:17]
	v_mov_b32_e32 v66, v126
	s_andn2_b64 exec, exec, s[84:85]
	s_cbranch_execz .LBB0_237
